# mix queue order: DIFF attention items dequeued before the shorter GQA items
# speedup vs baseline: 1.0046x; 1.0046x over previous
; __device__ void phase_mix(PP p, int l, unsigned char* smem, unsigned* counter, int first_item) {
;     ...
;   for (;;) {
;     __syncthreads();
;     if (ltid() == 0) *qslot = atomicAdd(counter, 1u);
;     __syncthreads();
;     const int it = (int)*qslot + first_item;
;     if (it >= nitems) break;
;     if (it < 1152) {
;       const int chain = it & 31, c = it >> 5; const int dir = chain & 1, h = (chain >> 1) & 3, b = chain >> 3;
;       dn_t_item(smem, (const float*)(ws + WS_DNQ), (const float*)(ws + WS_DNK), (const float*)(ws + WS_DNBG), ws + WS_DNIMG + ((size_t)chain * 36 + c) * 2 * DN_IMG, chain_cnt + chain, b, h, dir, c);
;     } else if (it < 1216) {
;       const int i2 = it - 1152; const int vh = i2 & 1, chain = i2 >> 1; const int dir = chain & 1, h = (chain >> 1) & 3, b = chain >> 3;
;       dn_scan_item(smem, (const float*)(ws + WS_DNQ), (const float*)(ws + WS_DNK), (const float*)(ws + WS_DNV), (const float*)(ws + WS_DNBG), ws + WS_DNIMG + (size_t)chain * 36 * 2 * DN_IMG, chain_cnt + chain,
;                    (float*)(ws + WS_DNO) + (size_t)dir * TT * 512, b, h, dir, vh, need_ctx);
;     } else if (it < 1280) {
;       const int i2 = it - 1216; const int dir = i2 & 1, hd = (i2 >> 1) & 7, b = i2 >> 4;
;       ssd_item(smem, (const float*)(ws + WS_SC), (const float*)(ws + WS_SB), (const float*)(ws + WS_SX), (const float*)(ws + WS_ST),
;                (float*)(ws + WS_SY) + (size_t)dir * TT * 512, b, hd, dir, need_ctx);
;     } else if (it < 1408 || (it >= 1664 && it < 1680)) {
;       int b, h, row0, nk;
;       if (it < 1408) { const int i2 = it - 1280; const int qt = i2 & 7; h = (i2 >> 3) & 3; b = i2 >> 5; row0 = b * SEQ + qt * 256; nk = NKEY; }
;       else { const int i2 = it - 1664; h = i2 & 3; b = i2 >> 2; row0 = NLAT + b * CTXL; nk = CTXL; }
;       ab::attn_body<true>((const bf16_t*)(ws + WS_GQ) + (size_t)row0 * 512 + h * 128, 512, (const bf16_t*)(ws + WS_GK) + (size_t)(b * 2 + (h >> 1)) * NKEY * 128,
;                           (const bf16_t*)(ws + WS_GVT) + (size_t)(b * 2 + (h >> 1)) * NKEY * 128, (bf16_t*)(ws + WS_MIX) + (size_t)row0 * D + 512 + h * 128, D, nk, (char*)smem);
;     } else {
;       int b, hm, row0, nk;
;       if (it < 1664) { const int i2 = it - 1408; const int qt = i2 & 7; hm = (i2 >> 3) & 7; b = i2 >> 6; row0 = b * SEQ + qt * 256; nk = NKEY; }
.LBB0_260:
	s_or_b64 exec, exec, s[4:5]
	v_readlane_b32 s3, v254, 8
	s_waitcnt lgkmcnt(0)
	s_barrier
	v_mov_b32_e32 v0, s3
	ds_read_b32 v0, v0
	s_mov_b64 s[4:5], -1
	s_waitcnt lgkmcnt(0)
	v_cmp_le_i32_e32 vcc, s0, v0
	v_readfirstlane_b32 s56, v0
	s_cbranch_vccnz .LBB0_255
	s_cmp_lt_u32 s56, 1280
	s_cbranch_scc1 .Lrm_done
	s_cmp_ge_u32 s56, 1664
	s_cbranch_scc1 .Lrm_done
	s_cmp_lt_u32 s56, 1536
	s_cbranch_scc1 .Lrm_c
	s_sub_u32 s56, s56, 256
	s_branch .Lrm_done
.Lrm_c:
	s_add_u32 s56, s56, 128
.Lrm_done:
	s_cmpk_gt_i32 s56, 0x47f
	s_cbranch_scc0 .LBB0_407
	s_cmpk_gt_u32 s56, 0x4bf
	s_cbranch_scc0 .LBB0_348
	s_cmpk_gt_u32 s56, 0x4ff
	s_cbranch_scc0 .LBB0_308
	s_cmpk_gt_u32 s56, 0x57f
	s_cselect_b64 s[8:9], -1, 0
	s_and_b32 s3, s56, 0x7ffffff0
	s_cmpk_lg_i32 s3, 0x680
	s_cselect_b64 s[4:5], -1, 0
	s_and_b64 s[6:7], s[8:9], s[4:5]
	s_mov_b64 s[4:5], -1
	s_and_b64 vcc, exec, s[6:7]
	s_cbranch_vccz .LBB0_289
	s_cmpk_gt_u32 s56, 0x67f
	s_cbranch_scc0 .LBB0_267
	s_add_i32 s3, s56, 0xfffff970
	s_ashr_i32 s6, s3, 3
	s_lshl_b32 s3, s6, 8
	s_add_i32 s40, s3, 0x2000
	s_mov_b64 s[4:5], 0
